# attention sub-step 1: next-tile LDS write block moved from in front of the Q.K MFMAs into the 12 mandatory wait states behind them (replaces s_nop 11); Q.K starts 11 issue slots earlier
# speedup vs baseline: 1.0028x; 1.0018x over previous
; __device__ __forceinline__ void attn_phase(const Args& a, int l, bool with_ctx, unsigned char* lds) {
;     ...
;                 const unsigned char* kb = lds + cur * BUF + c * 9216 + (32 * sub + r32) * 144 + hi * 16;
;                 const unsigned char* vb = lds + cur * BUF + KT + r32 * 144 + 64 * sub + hi * 16;
;                 bf16x8 kf[4], vf[8];
; #pragma unroll
;                 for (int d0 = 0; d0 < 4; ++d0) kf[d0] = *(const bf16x8*)(kb + d0 * 32);
; #pragma unroll
;                 for (int j = 0; j < 4; ++j) { vf[2 * j] = *(const bf16x8*)(vb + j * 32 * 144); vf[2 * j + 1] = *(const bf16x8*)(vb + j * 32 * 144 + 32); }
;                 __builtin_amdgcn_sched_barrier(0);
;                 f32x16 S;
; #pragma unroll
;                 for (int r = 0; r < 16; ++r) S[r] = negm;
; #pragma unroll
;                 for (int d0 = 0; d0 < 4; ++d0) S = MFMA32(kf[d0], qf[d0], S);
;                 float mx = S[0];
; #pragma unroll
;                 for (int r = 1; r < 16; ++r) mx = fmaxf(mx, S[r]);
;                 if (first || __any(mx > 8.f)) {
;                     mx = fmaxf(mx, __shfl_xor(mx, 32));
;                     const float dl = first ? mx : fmaxf(mx, 0.f); const float alpha = first ? 1.f : __builtin_amdgcn_exp2f(-dl); negm -= dl; lrun *= alpha; first = false;
; #pragma unroll
;                     for (int r = 0; r < 16; ++r) S[r] -= dl;
; #pragma unroll
;                     for (int j = 0; j < 4; ++j)
; #pragma unroll
;                         for (int r = 0; r < 16; ++r) O[j][r] *= alpha;
;                 }
;                 float ps = 0.f;
; #pragma unroll
;                 for (int r = 0; r < 16; ++r) { S[r] = __builtin_amdgcn_exp2f(S[r]); ps += S[r]; }
;                 lrun += ps;
;                 u32x4 p0, p1;
;                 p0.x = pk2(S[0], S[1]); p0.y = pk2(S[2], S[3]); p0.z = pk2(S[4], S[5]); p0.w = pk2(S[6], S[7]);
;                 p1.x = pk2(S[8], S[9]); p1.y = pk2(S[10], S[11]); p1.z = pk2(S[12], S[13]); p1.w = pk2(S[14], S[15]);
;                 const bf16x8 pa0 = __builtin_bit_cast(bf16x8, p0), pa1 = __builtin_bit_cast(bf16x8, p1);
; #pragma unroll
;                 for (int j = 0; j < 4; ++j) O[j] = MFMA32(vf[2 * j], pa0, O[j]);
; #pragma unroll
;                 for (int j = 0; j < 4; ++j) O[j] = MFMA32(vf[2 * j + 1], pa1, O[j]);
;             }
.LBB0_410:
	v_exp_f32_e32 v67, v68
	v_exp_f32_e32 v186, v69
	v_exp_f32_e32 v187, v70
	v_exp_f32_e32 v213, v71
	v_exp_f32_e32 v214, v72
	v_exp_f32_e32 v215, v73
	v_exp_f32_e32 v216, v74
	v_exp_f32_e32 v217, v75
	v_cvt_pk_bf16_f32 v68, v67, v186
	v_cvt_pk_bf16_f32 v69, v187, v213
	v_cvt_pk_bf16_f32 v70, v214, v215
	v_cvt_pk_bf16_f32 v71, v216, v217
	v_add_f32_e32 v67, 0, v67
	v_add_f32_e32 v67, v186, v67
	s_waitcnt lgkmcnt(7)
	v_mfma_f32_32x32x16_bf16 v[50:65], v[140:143], v[68:71], v[50:65]
	v_exp_f32_e32 v76, v76
	v_exp_f32_e32 v77, v77
	v_exp_f32_e32 v78, v78
	v_exp_f32_e32 v79, v79
	v_exp_f32_e32 v80, v80
	v_exp_f32_e32 v81, v81
	v_exp_f32_e32 v82, v82
	s_waitcnt lgkmcnt(5)
	v_mfma_f32_32x32x16_bf16 v[34:49], v[144:147], v[68:71], v[34:49]
	v_exp_f32_e32 v83, v83
	v_add_f32_e32 v67, v187, v67
	v_add_f32_e32 v67, v213, v67
	v_add_f32_e32 v67, v214, v67
	v_add_f32_e32 v67, v215, v67
	v_cvt_pk_bf16_f32 v72, v76, v77
	v_cvt_pk_bf16_f32 v73, v78, v79
	s_waitcnt lgkmcnt(3)
	v_mfma_f32_32x32x16_bf16 v[18:33], v[136:139], v[68:71], v[18:33]
	v_cvt_pk_bf16_f32 v74, v80, v81
	v_cvt_pk_bf16_f32 v75, v82, v83
	v_add_f32_e32 v67, v216, v67
	v_add_f32_e32 v67, v217, v67
	v_add_f32_e32 v67, v76, v67
	v_add_f32_e32 v67, v77, v67
	v_add_f32_e32 v67, v78, v67
	s_waitcnt lgkmcnt(1)
	v_mfma_f32_32x32x16_bf16 v[2:17], v[132:135], v[68:71], v[2:17]
	v_add_f32_e32 v67, v79, v67
	v_add_f32_e32 v67, v80, v67
	v_add_f32_e32 v67, v81, v67
	v_add_f32_e32 v67, v82, v67
	v_add_f32_e32 v67, v83, v67
	v_add_f32_e32 v171, v171, v67
	v_mfma_f32_32x32x16_bf16 v[50:65], v[128:131], v[72:75], v[50:65]
	v_mfma_f32_32x32x16_bf16 v[34:49], v[116:119], v[72:75], v[34:49]
	v_mfma_f32_32x32x16_bf16 v[18:33], v[120:123], v[72:75], v[18:33]
	s_waitcnt lgkmcnt(0)
	v_mfma_f32_32x32x16_bf16 v[2:17], v[124:127], v[72:75], v[2:17]
	ds_read_b128 v[214:217], v185 offset:4608
	ds_read_b128 v[218:221], v185 offset:4640
	ds_read_b128 v[222:225], v185 offset:4672
	ds_read_b128 v[226:229], v185 offset:4704
	ds_read_b128 v[136:139], v184 offset:18496
	ds_read_b128 v[116:119], v184 offset:18528
	ds_read_b128 v[140:143], v184 offset:23104
	ds_read_b128 v[120:123], v184 offset:23136
	ds_read_b128 v[144:147], v184 offset:27712
	ds_read_b128 v[124:127], v184 offset:27744
	ds_read_b128 v[132:135], v184 offset:32320
	ds_read_b128 v[128:131], v184 offset:32352
	s_waitcnt lgkmcnt(11)
	s_nop 0
	v_mfma_f32_32x32x16_bf16 v[68:83], v[214:217], v[84:87], v[230:245]
	s_waitcnt lgkmcnt(10)
	v_mfma_f32_32x32x16_bf16 v[68:83], v[218:221], v[88:91], v[68:83]
	s_waitcnt lgkmcnt(9)
	v_mfma_f32_32x32x16_bf16 v[68:83], v[222:225], v[92:95], v[68:83]
	s_waitcnt lgkmcnt(8)
	v_mfma_f32_32x32x16_bf16 v[68:83], v[226:229], v[96:99], v[68:83]
	s_xor_b32 s22, s15, 1
	s_mul_i32 s22, s22, 0x9000
	v_add_u32_e32 v246, s22, v176
	s_waitcnt vmcnt(3)
	ds_write_b128 v246, v[100:103]
	s_waitcnt vmcnt(2)
	ds_write_b128 v246, v[104:107] offset:9216
	s_waitcnt vmcnt(1)
	ds_write_b128 v246, v[108:111] offset:18432
	s_waitcnt vmcnt(0)
	ds_write_b128 v246, v[112:115] offset:27648
	s_nop 0
	v_max_f32_e32 v67, v69, v69
	v_max_f32_e32 v184, v68, v68
	v_max_f32_e32 v67, v184, v67
	v_max3_f32 v67, v67, v70, v71
	v_max3_f32 v67, v67, v72, v73
	v_max3_f32 v67, v67, v74, v75
	v_max3_f32 v67, v67, v76, v77
	v_max3_f32 v67, v67, v78, v79
	v_max3_f32 v67, v67, v80, v81
	v_max3_f32 v67, v67, v82, v83
	v_cmp_lt_f32_e32 vcc, s68, v67
	s_cbranch_vccz .LBB0_412
	ds_bpermute_b32 v184, v180, v67
	s_waitcnt lgkmcnt(0)
	v_max3_f32 v184, v67, v184, 0
	v_exp_f32_e64 v186, -v184
	v_sub_f32_e32 v66, v66, v184
	v_mov_b32_e32 v230, v66
	v_mov_b32_e32 v231, v66
	v_mov_b32_e32 v232, v66
	v_mov_b32_e32 v233, v66
	v_mov_b32_e32 v234, v66
	v_mov_b32_e32 v235, v66
	v_mov_b32_e32 v236, v66
	v_mov_b32_e32 v237, v66
	v_mov_b32_e32 v238, v66
	v_mov_b32_e32 v239, v66
	v_mov_b32_e32 v240, v66
	v_mov_b32_e32 v241, v66
	v_mov_b32_e32 v242, v66
	v_mov_b32_e32 v243, v66
	v_mov_b32_e32 v244, v66
	v_mov_b32_e32 v245, v66
	v_pk_add_f32 v[68:69], v[68:69], v[184:185] op_sel_hi:[1,0] neg_lo:[0,1] neg_hi:[0,1]
	v_pk_add_f32 v[70:71], v[70:71], v[184:185] op_sel_hi:[1,0] neg_lo:[0,1] neg_hi:[0,1]
	v_pk_add_f32 v[72:73], v[72:73], v[184:185] op_sel_hi:[1,0] neg_lo:[0,1] neg_hi:[0,1]
	v_pk_add_f32 v[74:75], v[74:75], v[184:185] op_sel_hi:[1,0] neg_lo:[0,1] neg_hi:[0,1]
	v_pk_add_f32 v[76:77], v[76:77], v[184:185] op_sel_hi:[1,0] neg_lo:[0,1] neg_hi:[0,1]
	v_pk_add_f32 v[78:79], v[78:79], v[184:185] op_sel_hi:[1,0] neg_lo:[0,1] neg_hi:[0,1]
	v_pk_add_f32 v[80:81], v[80:81], v[184:185] op_sel_hi:[1,0] neg_lo:[0,1] neg_hi:[0,1]
	v_pk_add_f32 v[82:83], v[82:83], v[184:185] op_sel_hi:[1,0] neg_lo:[0,1] neg_hi:[0,1]
	v_pk_mul_f32 v[64:65], v[64:65], v[186:187] op_sel_hi:[1,0]
	v_pk_mul_f32 v[62:63], v[62:63], v[186:187] op_sel_hi:[1,0]
	v_pk_mul_f32 v[60:61], v[60:61], v[186:187] op_sel_hi:[1,0]
	v_pk_mul_f32 v[58:59], v[58:59], v[186:187] op_sel_hi:[1,0]
	v_pk_mul_f32 v[56:57], v[56:57], v[186:187] op_sel_hi:[1,0]
	v_pk_mul_f32 v[54:55], v[54:55], v[186:187] op_sel_hi:[1,0]
	v_pk_mul_f32 v[52:53], v[52:53], v[186:187] op_sel_hi:[1,0]
	v_pk_mul_f32 v[50:51], v[50:51], v[186:187] op_sel_hi:[1,0]
	v_pk_mul_f32 v[48:49], v[48:49], v[186:187] op_sel_hi:[1,0]
	v_pk_mul_f32 v[46:47], v[46:47], v[186:187] op_sel_hi:[1,0]
	v_pk_mul_f32 v[44:45], v[44:45], v[186:187] op_sel_hi:[1,0]
	v_pk_mul_f32 v[42:43], v[42:43], v[186:187] op_sel_hi:[1,0]
	v_pk_mul_f32 v[40:41], v[40:41], v[186:187] op_sel_hi:[1,0]
	v_pk_mul_f32 v[38:39], v[38:39], v[186:187] op_sel_hi:[1,0]
	v_pk_mul_f32 v[36:37], v[36:37], v[186:187] op_sel_hi:[1,0]
	v_pk_mul_f32 v[34:35], v[34:35], v[186:187] op_sel_hi:[1,0]
	v_pk_mul_f32 v[32:33], v[32:33], v[186:187] op_sel_hi:[1,0]
	v_pk_mul_f32 v[30:31], v[30:31], v[186:187] op_sel_hi:[1,0]
	v_pk_mul_f32 v[28:29], v[28:29], v[186:187] op_sel_hi:[1,0]
	v_pk_mul_f32 v[26:27], v[26:27], v[186:187] op_sel_hi:[1,0]
	v_pk_mul_f32 v[24:25], v[24:25], v[186:187] op_sel_hi:[1,0]
	v_pk_mul_f32 v[22:23], v[22:23], v[186:187] op_sel_hi:[1,0]
	v_pk_mul_f32 v[20:21], v[20:21], v[186:187] op_sel_hi:[1,0]
	v_pk_mul_f32 v[18:19], v[18:19], v[186:187] op_sel_hi:[1,0]
	v_pk_mul_f32 v[16:17], v[16:17], v[186:187] op_sel_hi:[1,0]
	v_pk_mul_f32 v[14:15], v[14:15], v[186:187] op_sel_hi:[1,0]
	v_pk_mul_f32 v[12:13], v[12:13], v[186:187] op_sel_hi:[1,0]
	v_pk_mul_f32 v[10:11], v[10:11], v[186:187] op_sel_hi:[1,0]
	v_pk_mul_f32 v[8:9], v[8:9], v[186:187] op_sel_hi:[1,0]
	v_pk_mul_f32 v[6:7], v[6:7], v[186:187] op_sel_hi:[1,0]
	v_pk_mul_f32 v[4:5], v[4:5], v[186:187] op_sel_hi:[1,0]
	v_pk_mul_f32 v[2:3], v[2:3], v[186:187] op_sel_hi:[1,0]
	v_mul_f32_e32 v171, v171, v186
